# counted lgkmcnt waits in the four GEMM K-loops (reads pipelined one MFMA block ahead)
# speedup vs baseline: 1.0069x; 1.0069x over previous
; #define WAIT_V0() asm volatile("s_waitcnt vmcnt(0)" ::: "memory")
; #define G_STAGE_A(Ap, buf, kt) do { const char* ab_ = (const char*)(Ap) + (size_t)(kt) * 128; \
;       _Pragma("unroll") for (int i = 0; i < 4; ++i) \
;         __builtin_amdgcn_global_load_lds((const unsigned*)(ab_ + soff[i]), (LDSP unsigned*)(G_SA(buf) + wid * 1024 + i * 8192), 16, 0, 0); } while (0)
; #define G_STAGE_B(Bp, buf, kt) do { const char* bb_ = (const char*)(Bp) + (size_t)(kt) * 128; \
;       _Pragma("unroll") for (int i = 0; i < 4; ++i) \
;         __builtin_amdgcn_global_load_lds((const unsigned*)(bb_ + soff[i]), (LDSP unsigned*)(G_SB(buf) + wid * 1024 + i * 8192), 16, 0, 0); } while (0)
; #define G_RDA(AF, buf, ks, mh) do { _Pragma("unroll") for (int m = 0; m < 4; ++m) AF[m] = *(const LDSP bf16x8*)(G_SA(buf) + aoff + ((mh) * 4 + m) * 2048 + (ks) * 1024); } while (0)
; #define G_RDB(BF, buf, ks) do { _Pragma("unroll") for (int n = 0; n < 4; ++n) BF[n] = *(const LDSP bf16x8*)(G_SB(buf) + boff + n * 2048 + (ks) * 1024); } while (0)
; #define G_MMA(AF, BF, mh) do { __builtin_amdgcn_s_setprio(1); \
;             _Pragma("unroll") for (int m = 0; m < 4; ++m) _Pragma("unroll") for (int n = 0; n < 4; ++n) \
;                 acc[(mh) * 4 + m][n] = __builtin_amdgcn_mfma_f32_16x16x32_bf16(BF[n], AF[m], acc[(mh) * 4 + m][n], 0, 0, 0); \
;             __builtin_amdgcn_s_setprio(0); } while (0)
; template <int EK>
; DI void gemm_stream(const Params& p, int l, const bf16_t* __restrict__ A, const bf16_t* __restrict__ Bt, int M, int N, int K, ldsp_t shm) {
;     ...
;         for (int t = 0; t < nt; ++t) {
;             const int cur = t & 1;
;             G_RDA(Aa, cur, 0, 0); G_RDB(Bk0, cur, 0);
;             if (t + 1 < nt) G_STAGE_B(Bb, cur ^ 1, t + 1);
;             else if (has_next) G_STAGE_B(Bb2, cur ^ 1, 0);
;             G_SB0();
;             if (t > 0) G_MMA(Ab_, Bk1, 1);
;             G_SB0();
;             if (t + 1 < nt) G_STAGE_A(Ab, cur ^ 1, t + 1);
;             else if (has_next) G_STAGE_A(Ab2, cur ^ 1, 0);
;             G_RDA(Ab_, cur, 0, 1);
;             G_MMA(Aa, Bk0, 0); G_SB0();
;             G_RDA(Aa, cur, 1, 0); G_RDB(Bk1, cur, 1);
;             G_MMA(Ab_, Bk0, 1); G_SB0();
;             G_RDA(Ab_, cur, 1, 1);
;             G_MMA(Aa, Bk1, 0); G_SB0();
;             asm volatile("s_waitcnt lgkmcnt(0)" ::: "memory");
;             WAIT_V0(); __syncthreads();
;         }
.LBB0_111:
	s_and_b32 s37, s35, 0x10000
	v_add_u32_e32 v221, s37, v218
	v_or_b32_e32 v226, s37, v219
	s_xor_b32 s37, s37, 0x10000
	v_add_u32_e32 v227, s37, v220
	v_add_u32_e32 v228, 0x8000, v227
	v_lshl_add_u64 v[200:201], v[160:161], 0, s[4:5]
	v_readfirstlane_b32 s37, v228
	v_add_u32_e32 v228, 0xa000, v227
	s_mov_b32 m0, s37
	v_readfirstlane_b32 s37, v228
	v_add_u32_e32 v228, 0xc000, v227
	ds_read_b128 v[176:179], v221
	ds_read_b128 v[180:183], v221 offset:2048
	ds_read_b128 v[184:187], v221 offset:4096
	ds_read_b128 v[188:191], v221 offset:6144
	ds_read_b128 v[204:207], v226 offset:32768
	ds_read_b128 v[210:213], v226 offset:34816
	ds_read_b128 v[214:217], v226 offset:36864
	ds_read_b128 v[222:225], v226 offset:38912
	global_load_lds_dwordx4 v[200:201], off
	v_lshl_add_u64 v[200:201], v[162:163], 0, s[4:5]
	s_mov_b32 m0, s37
	v_readfirstlane_b32 s37, v228
	v_add_u32_e32 v228, 0xe000, v227
	global_load_lds_dwordx4 v[200:201], off
	v_lshl_add_u64 v[200:201], v[164:165], 0, s[4:5]
	s_mov_b32 m0, s37
	v_readfirstlane_b32 s37, v228
	global_load_lds_dwordx4 v[200:201], off
	v_lshl_add_u64 v[200:201], v[166:167], 0, s[4:5]
	s_mov_b32 m0, s37
	s_nop 0
	global_load_lds_dwordx4 v[200:201], off
	s_setprio 1
	v_mfma_f32_16x16x32_bf16 v[128:131], v[64:67], v[156:159], v[128:131]
	v_mfma_f32_16x16x32_bf16 v[124:127], v[68:71], v[156:159], v[124:127]
	v_mfma_f32_16x16x32_bf16 v[120:123], v[76:79], v[156:159], v[120:123]
	v_mfma_f32_16x16x32_bf16 v[116:119], v[72:75], v[156:159], v[116:119]
	v_mfma_f32_16x16x32_bf16 v[112:115], v[64:67], v[152:155], v[112:115]
	v_mfma_f32_16x16x32_bf16 v[108:111], v[68:71], v[152:155], v[108:111]
	v_mfma_f32_16x16x32_bf16 v[104:107], v[76:79], v[152:155], v[104:107]
	v_mfma_f32_16x16x32_bf16 v[100:103], v[72:75], v[152:155], v[100:103]
	v_mfma_f32_16x16x32_bf16 v[96:99], v[64:67], v[148:151], v[96:99]
	v_mfma_f32_16x16x32_bf16 v[92:95], v[68:71], v[148:151], v[92:95]
	v_mfma_f32_16x16x32_bf16 v[88:91], v[76:79], v[148:151], v[88:91]
	v_mfma_f32_16x16x32_bf16 v[84:87], v[72:75], v[148:151], v[84:87]
	v_mfma_f32_16x16x32_bf16 v[132:135], v[64:67], v[144:147], v[132:135]
	v_mfma_f32_16x16x32_bf16 v[136:139], v[68:71], v[144:147], v[136:139]
	v_mfma_f32_16x16x32_bf16 v[140:143], v[76:79], v[144:147], v[140:143]
	v_mfma_f32_16x16x32_bf16 v[80:83], v[72:75], v[144:147], v[80:83]
	s_setprio 0
	v_readfirstlane_b32 s37, v227
	v_add_u32_e32 v66, 0x2000, v227
	v_lshl_add_u64 v[64:65], v[168:169], 0, s[4:5]
	s_mov_b32 m0, s37
	v_readfirstlane_b32 s37, v66
	v_add_u32_e32 v66, 0x4000, v227
	global_load_lds_dwordx4 v[64:65], off
	v_lshl_add_u64 v[64:65], v[170:171], 0, s[4:5]
	s_mov_b32 m0, s37
	v_readfirstlane_b32 s37, v66
	v_add_u32_e32 v66, 0x6000, v227
	global_load_lds_dwordx4 v[64:65], off
	v_lshl_add_u64 v[64:65], v[172:173], 0, s[4:5]
	s_mov_b32 m0, s37
	v_readfirstlane_b32 s37, v66
	global_load_lds_dwordx4 v[64:65], off
	v_lshl_add_u64 v[64:65], v[174:175], 0, s[4:5]
	s_mov_b32 m0, s37
	s_nop 0
	global_load_lds_dwordx4 v[64:65], off
	ds_read_b128 v[144:147], v221 offset:8192
	ds_read_b128 v[148:151], v221 offset:10240
	ds_read_b128 v[152:155], v221 offset:12288
	ds_read_b128 v[156:159], v221 offset:14336
	s_setprio 1
	s_waitcnt lgkmcnt(4)
	v_mfma_f32_16x16x32_bf16 v[60:63], v[204:207], v[176:179], v[60:63]
	v_mfma_f32_16x16x32_bf16 v[56:59], v[210:213], v[176:179], v[56:59]
	v_mfma_f32_16x16x32_bf16 v[52:55], v[214:217], v[176:179], v[52:55]
	v_mfma_f32_16x16x32_bf16 v[48:51], v[222:225], v[176:179], v[48:51]
	v_mfma_f32_16x16x32_bf16 v[44:47], v[204:207], v[180:183], v[44:47]
	v_mfma_f32_16x16x32_bf16 v[40:43], v[210:213], v[180:183], v[40:43]
	v_mfma_f32_16x16x32_bf16 v[36:39], v[214:217], v[180:183], v[36:39]
	v_mfma_f32_16x16x32_bf16 v[32:35], v[222:225], v[180:183], v[32:35]
	v_mfma_f32_16x16x32_bf16 v[28:31], v[204:207], v[184:187], v[28:31]
	v_mfma_f32_16x16x32_bf16 v[24:27], v[210:213], v[184:187], v[24:27]
	v_mfma_f32_16x16x32_bf16 v[20:23], v[214:217], v[184:187], v[20:23]
	v_mfma_f32_16x16x32_bf16 v[16:19], v[222:225], v[184:187], v[16:19]
	v_mfma_f32_16x16x32_bf16 v[12:15], v[204:207], v[188:191], v[12:15]
	v_mfma_f32_16x16x32_bf16 v[8:11], v[210:213], v[188:191], v[8:11]
	v_mfma_f32_16x16x32_bf16 v[4:7], v[214:217], v[188:191], v[4:7]
	v_mfma_f32_16x16x32_bf16 v[0:3], v[222:225], v[188:191], v[0:3]
	s_setprio 0
	ds_read_b128 v[176:179], v221 offset:1024
	ds_read_b128 v[180:183], v221 offset:3072
	ds_read_b128 v[184:187], v221 offset:5120
	ds_read_b128 v[188:191], v221 offset:7168
	ds_read_b128 v[64:67], v226 offset:33792
	ds_read_b128 v[68:71], v226 offset:35840
	ds_read_b128 v[76:79], v226 offset:37888
	ds_read_b128 v[72:75], v226 offset:39936
	s_setprio 1
	s_waitcnt lgkmcnt(8)
; #define WAIT_V0() asm volatile("s_waitcnt vmcnt(0)" ::: "memory")
; #define G_STAGE_B(Bp, buf, kt) do { const char* bb_ = (const char*)(Bp) + (size_t)(kt) * 128; \
;       _Pragma("unroll") for (int i = 0; i < 4; ++i) \
;         __builtin_amdgcn_global_load_lds((const unsigned*)(bb_ + soff[i]), (LDSP unsigned*)(G_SB(buf) + wid * 1024 + i * 8192), 16, 0, 0); } while (0)
; #define G_RDA(AF, buf, ks, mh) do { _Pragma("unroll") for (int m = 0; m < 4; ++m) AF[m] = *(const LDSP bf16x8*)(G_SA(buf) + aoff + ((mh) * 4 + m) * 2048 + (ks) * 1024); } while (0)
; #define G_RDB(BF, buf, ks) do { _Pragma("unroll") for (int n = 0; n < 4; ++n) BF[n] = *(const LDSP bf16x8*)(G_SB(buf) + boff + n * 2048 + (ks) * 1024); } while (0)
; #define G_MMA(AF, BF, mh) do { __builtin_amdgcn_s_setprio(1); \
;             _Pragma("unroll") for (int m = 0; m < 4; ++m) _Pragma("unroll") for (int n = 0; n < 4; ++n) \
;                 acc[(mh) * 4 + m][n] = __builtin_amdgcn_mfma_f32_16x16x32_bf16(BF[n], AF[m], acc[(mh) * 4 + m][n], 0, 0, 0); \
;             __builtin_amdgcn_s_setprio(0); } while (0)
; #define G_SB0() __builtin_amdgcn_sched_barrier(0)
; template <int EK>
; DI void gemm_stream(const Params& p, int l, const bf16_t* __restrict__ A, const bf16_t* __restrict__ Bt, int M, int N, int K, ldsp_t shm) {
;     ...
;             G_RDA(Aa, cur, 0, 0); G_RDB(Bk0, cur, 0);
;             if (t + 1 < nt) G_STAGE_B(Bb, cur ^ 1, t + 1);
;             else if (has_next) G_STAGE_B(Bb2, cur ^ 1, 0);
;     ...
;             G_RDA(Aa, cur, 1, 0); G_RDB(Bk1, cur, 1);
;             G_MMA(Ab_, Bk0, 1); G_SB0();
;             G_RDA(Ab_, cur, 1, 1);
;             G_MMA(Aa, Bk1, 0); G_SB0();
;             asm volatile("s_waitcnt lgkmcnt(0)" ::: "memory");
;             WAIT_V0(); __syncthreads();
;         }
	v_mfma_f32_16x16x32_bf16 v[128:131], v[204:207], v[144:147], v[128:131]
	v_mfma_f32_16x16x32_bf16 v[124:127], v[210:213], v[144:147], v[124:127]
	v_mfma_f32_16x16x32_bf16 v[120:123], v[214:217], v[144:147], v[120:123]
	v_mfma_f32_16x16x32_bf16 v[116:119], v[222:225], v[144:147], v[116:119]
	v_mfma_f32_16x16x32_bf16 v[112:115], v[204:207], v[148:151], v[112:115]
	v_mfma_f32_16x16x32_bf16 v[108:111], v[210:213], v[148:151], v[108:111]
	v_mfma_f32_16x16x32_bf16 v[104:107], v[214:217], v[148:151], v[104:107]
	v_mfma_f32_16x16x32_bf16 v[100:103], v[222:225], v[148:151], v[100:103]
	v_mfma_f32_16x16x32_bf16 v[96:99], v[204:207], v[152:155], v[96:99]
	v_mfma_f32_16x16x32_bf16 v[92:95], v[210:213], v[152:155], v[92:95]
	v_mfma_f32_16x16x32_bf16 v[88:91], v[214:217], v[152:155], v[88:91]
	v_mfma_f32_16x16x32_bf16 v[84:87], v[222:225], v[152:155], v[84:87]
	v_mfma_f32_16x16x32_bf16 v[132:135], v[204:207], v[156:159], v[132:135]
	v_mfma_f32_16x16x32_bf16 v[136:139], v[210:213], v[156:159], v[136:139]
	v_mfma_f32_16x16x32_bf16 v[140:143], v[214:217], v[156:159], v[140:143]
	v_mfma_f32_16x16x32_bf16 v[80:83], v[222:225], v[156:159], v[80:83]
	s_setprio 0
	ds_read_b128 v[156:159], v221 offset:9216
	ds_read_b128 v[152:155], v221 offset:11264
	ds_read_b128 v[148:151], v221 offset:13312
	ds_read_b128 v[144:147], v221 offset:15360
	s_setprio 1
	s_waitcnt lgkmcnt(4)
	v_mfma_f32_16x16x32_bf16 v[60:63], v[64:67], v[176:179], v[60:63]
	v_mfma_f32_16x16x32_bf16 v[56:59], v[68:71], v[176:179], v[56:59]
	v_mfma_f32_16x16x32_bf16 v[52:55], v[76:79], v[176:179], v[52:55]
	v_mfma_f32_16x16x32_bf16 v[48:51], v[72:75], v[176:179], v[48:51]
	v_mfma_f32_16x16x32_bf16 v[44:47], v[64:67], v[180:183], v[44:47]
	v_mfma_f32_16x16x32_bf16 v[40:43], v[68:71], v[180:183], v[40:43]
	v_mfma_f32_16x16x32_bf16 v[36:39], v[76:79], v[180:183], v[36:39]
	v_mfma_f32_16x16x32_bf16 v[32:35], v[72:75], v[180:183], v[32:35]
	v_mfma_f32_16x16x32_bf16 v[28:31], v[64:67], v[184:187], v[28:31]
	v_mfma_f32_16x16x32_bf16 v[24:27], v[68:71], v[184:187], v[24:27]
	v_mfma_f32_16x16x32_bf16 v[20:23], v[76:79], v[184:187], v[20:23]
	v_mfma_f32_16x16x32_bf16 v[16:19], v[72:75], v[184:187], v[16:19]
	v_mfma_f32_16x16x32_bf16 v[12:15], v[64:67], v[188:191], v[12:15]
	v_mfma_f32_16x16x32_bf16 v[8:11], v[68:71], v[188:191], v[8:11]
	v_mfma_f32_16x16x32_bf16 v[4:7], v[76:79], v[188:191], v[4:7]
	v_mfma_f32_16x16x32_bf16 v[0:3], v[72:75], v[188:191], v[0:3]
	s_setprio 0
	s_waitcnt lgkmcnt(0)
	s_waitcnt vmcnt(0)
	s_add_u32 s4, s4, 0x80
	s_addc_u32 s5, s5, 0
	s_add_i32 s35, s35, 0x10000
	s_cmpk_eq_i32 s4, 0x700
	s_waitcnt vmcnt(0)
	s_barrier
	s_cbranch_scc0 .LBB0_111
	v_add_u32_e32 v160, 0x10000, v218
	v_add_u32_e32 v161, 0x10800, v218
	ds_read_b128 v[188:191], v160
	ds_read_b128 v[180:183], v161
	v_add_u32_e32 v160, 0x11000, v218
	v_add_u32_e32 v161, 0x11800, v218
	ds_read_b128 v[184:187], v160
	ds_read_b128 v[176:179], v161
	v_or_b32_e32 v160, 0x18000, v219
	v_add_u32_e32 v164, 0x18800, v219
	v_add_u32_e32 v168, 0x19000, v219
	v_add_u32_e32 v172, 0x19800, v219
	ds_read_b128 v[160:163], v160
	ds_read_b128 v[164:167], v164
	ds_read_b128 v[168:171], v168
	ds_read_b128 v[172:175], v172
	s_ashr_i32 s37, s36, 31
	v_cndmask_b32_e64 v200, 0, 1, s[42:43]
	v_cmp_ne_u32_e64 s[4:5], 1, v200
	s_andn2_b64 vcc, exec, s[42:43]
	s_lshl_b64 s[38:39], s[36:37], 19
	s_cbranch_vccnz .LBB0_114
	s_add_u32 s40, s9, s38
	v_add_u32_e32 v212, 0x8000, v220
	s_addc_u32 s41, s45, s39
	v_add_u32_e32 v215, 0xa000, v220
	v_readfirstlane_b32 s35, v212
	v_lshl_add_u64 v[200:201], s[40:41], 0, v[192:193]
	v_add_u32_e32 v214, 0xc000, v220
	s_mov_b32 m0, s35
	v_readfirstlane_b32 s35, v215
	v_lshl_add_u64 v[204:205], s[40:41], 0, v[194:195]
	v_add_u32_e32 v213, 0xe000, v220
	global_load_lds_dwordx4 v[200:201], off
	s_mov_b32 m0, s35
	v_readfirstlane_b32 s35, v214
	v_lshl_add_u64 v[206:207], s[40:41], 0, v[196:197]
	global_load_lds_dwordx4 v[204:205], off
	s_mov_b32 m0, s35
	v_readfirstlane_b32 s35, v213
	v_lshl_add_u64 v[210:211], s[40:41], 0, v[198:199]
	global_load_lds_dwordx4 v[206:207], off
	s_mov_b32 m0, s35
	s_nop 0
	global_load_lds_dwordx4 v[210:211], off

; #define WAIT_V0() asm volatile("s_waitcnt vmcnt(0)" ::: "memory")
; #define G_STAGE_A(Ap, buf, kt) do { const char* ab_ = (const char*)(Ap) + (size_t)(kt) * 128; \
;       _Pragma("unroll") for (int i = 0; i < 4; ++i) \
;         __builtin_amdgcn_global_load_lds((const unsigned*)(ab_ + soff[i]), (LDSP unsigned*)(G_SA(buf) + wid * 1024 + i * 8192), 16, 0, 0); } while (0)
; #define G_STAGE_B(Bp, buf, kt) do { const char* bb_ = (const char*)(Bp) + (size_t)(kt) * 128; \
;       _Pragma("unroll") for (int i = 0; i < 4; ++i) \
;         __builtin_amdgcn_global_load_lds((const unsigned*)(bb_ + soff[i]), (LDSP unsigned*)(G_SB(buf) + wid * 1024 + i * 8192), 16, 0, 0); } while (0)
; #define G_RDA(AF, buf, ks, mh) do { _Pragma("unroll") for (int m = 0; m < 4; ++m) AF[m] = *(const LDSP bf16x8*)(G_SA(buf) + aoff + ((mh) * 4 + m) * 2048 + (ks) * 1024); } while (0)
; #define G_RDB(BF, buf, ks) do { _Pragma("unroll") for (int n = 0; n < 4; ++n) BF[n] = *(const LDSP bf16x8*)(G_SB(buf) + boff + n * 2048 + (ks) * 1024); } while (0)
; #define G_MMA(AF, BF, mh) do { __builtin_amdgcn_s_setprio(1); \
;             _Pragma("unroll") for (int m = 0; m < 4; ++m) _Pragma("unroll") for (int n = 0; n < 4; ++n) \
;                 acc[(mh) * 4 + m][n] = __builtin_amdgcn_mfma_f32_16x16x32_bf16(BF[n], AF[m], acc[(mh) * 4 + m][n], 0, 0, 0); \
;             __builtin_amdgcn_s_setprio(0); } while (0)
; template <int EK>
; DI void gemm_stream(const Params& p, int l, const bf16_t* __restrict__ A, const bf16_t* __restrict__ Bt, int M, int N, int K, ldsp_t shm) {
;     ...
;         for (int t = 0; t < nt; ++t) {
;             const int cur = t & 1;
;             G_RDA(Aa, cur, 0, 0); G_RDB(Bk0, cur, 0);
;             if (t + 1 < nt) G_STAGE_B(Bb, cur ^ 1, t + 1);
;             else if (has_next) G_STAGE_B(Bb2, cur ^ 1, 0);
;             G_SB0();
;             if (t > 0) G_MMA(Ab_, Bk1, 1);
;             G_SB0();
;             if (t + 1 < nt) G_STAGE_A(Ab, cur ^ 1, t + 1);
;             else if (has_next) G_STAGE_A(Ab2, cur ^ 1, 0);
;             G_RDA(Ab_, cur, 0, 1);
;             G_MMA(Aa, Bk0, 0); G_SB0();
;             G_RDA(Aa, cur, 1, 0); G_RDB(Bk1, cur, 1);
;             G_MMA(Ab_, Bk0, 1); G_SB0();
;             G_RDA(Ab_, cur, 1, 1);
;             G_MMA(Aa, Bk1, 0); G_SB0();
;             asm volatile("s_waitcnt lgkmcnt(0)" ::: "memory");
;             WAIT_V0(); __syncthreads();
;         }
.LBB0_132:
	s_and_b32 s43, s41, 0x10000
	v_add_u32_e32 v221, s43, v218
	v_or_b32_e32 v226, s43, v219
	s_xor_b32 s43, s43, 0x10000
	v_add_u32_e32 v227, s43, v220
	v_add_u32_e32 v228, 0x8000, v227
	v_lshl_add_u64 v[200:201], v[160:161], 0, s[6:7]
	v_readfirstlane_b32 s43, v228
	v_add_u32_e32 v228, 0xa000, v227
	s_mov_b32 m0, s43
	v_readfirstlane_b32 s43, v228
	v_add_u32_e32 v228, 0xc000, v227
	ds_read_b128 v[176:179], v221
	ds_read_b128 v[180:183], v221 offset:2048
	ds_read_b128 v[184:187], v221 offset:4096
	ds_read_b128 v[188:191], v221 offset:6144
	ds_read_b128 v[204:207], v226 offset:32768
	ds_read_b128 v[210:213], v226 offset:34816
	ds_read_b128 v[214:217], v226 offset:36864
	ds_read_b128 v[222:225], v226 offset:38912
	global_load_lds_dwordx4 v[200:201], off
	v_lshl_add_u64 v[200:201], v[162:163], 0, s[6:7]
	s_mov_b32 m0, s43
	v_readfirstlane_b32 s43, v228
	v_add_u32_e32 v228, 0xe000, v227
	global_load_lds_dwordx4 v[200:201], off
	v_lshl_add_u64 v[200:201], v[164:165], 0, s[6:7]
	s_mov_b32 m0, s43
	v_readfirstlane_b32 s43, v228
	global_load_lds_dwordx4 v[200:201], off
	v_lshl_add_u64 v[200:201], v[166:167], 0, s[6:7]
	s_mov_b32 m0, s43
	s_nop 0
	global_load_lds_dwordx4 v[200:201], off
	s_setprio 1
	v_mfma_f32_16x16x32_bf16 v[140:143], v[64:67], v[156:159], v[140:143]
	v_mfma_f32_16x16x32_bf16 v[136:139], v[68:71], v[156:159], v[136:139]
	v_mfma_f32_16x16x32_bf16 v[132:135], v[72:75], v[156:159], v[132:135]
	v_mfma_f32_16x16x32_bf16 v[128:131], v[76:79], v[156:159], v[128:131]
	v_mfma_f32_16x16x32_bf16 v[124:127], v[64:67], v[152:155], v[124:127]
	v_mfma_f32_16x16x32_bf16 v[120:123], v[68:71], v[152:155], v[120:123]
	v_mfma_f32_16x16x32_bf16 v[116:119], v[72:75], v[152:155], v[116:119]
	v_mfma_f32_16x16x32_bf16 v[112:115], v[76:79], v[152:155], v[112:115]
	v_mfma_f32_16x16x32_bf16 v[108:111], v[64:67], v[148:151], v[108:111]
	v_mfma_f32_16x16x32_bf16 v[104:107], v[68:71], v[148:151], v[104:107]
	v_mfma_f32_16x16x32_bf16 v[100:103], v[72:75], v[148:151], v[100:103]
	v_mfma_f32_16x16x32_bf16 v[96:99], v[76:79], v[148:151], v[96:99]
	v_mfma_f32_16x16x32_bf16 v[92:95], v[64:67], v[144:147], v[92:95]
	v_mfma_f32_16x16x32_bf16 v[88:91], v[68:71], v[144:147], v[88:91]
	v_mfma_f32_16x16x32_bf16 v[84:87], v[72:75], v[144:147], v[84:87]
	v_mfma_f32_16x16x32_bf16 v[80:83], v[76:79], v[144:147], v[80:83]
	s_setprio 0
	v_readfirstlane_b32 s43, v227
	v_add_u32_e32 v66, 0x2000, v227
	v_lshl_add_u64 v[64:65], v[168:169], 0, s[6:7]
	s_mov_b32 m0, s43
	v_readfirstlane_b32 s43, v66
	v_add_u32_e32 v66, 0x4000, v227
	global_load_lds_dwordx4 v[64:65], off
	v_lshl_add_u64 v[64:65], v[170:171], 0, s[6:7]
	s_mov_b32 m0, s43
	v_readfirstlane_b32 s43, v66
	v_add_u32_e32 v66, 0x6000, v227
	global_load_lds_dwordx4 v[64:65], off
	v_lshl_add_u64 v[64:65], v[172:173], 0, s[6:7]
	s_mov_b32 m0, s43
	v_readfirstlane_b32 s43, v66
	global_load_lds_dwordx4 v[64:65], off
	v_lshl_add_u64 v[64:65], v[174:175], 0, s[6:7]
	s_mov_b32 m0, s43
	s_nop 0
	global_load_lds_dwordx4 v[64:65], off
	ds_read_b128 v[144:147], v221 offset:8192
	ds_read_b128 v[148:151], v221 offset:10240
	ds_read_b128 v[152:155], v221 offset:12288
	ds_read_b128 v[156:159], v221 offset:14336
	s_setprio 1
	s_waitcnt lgkmcnt(4)
	v_mfma_f32_16x16x32_bf16 v[0:3], v[204:207], v[176:179], v[0:3]
	v_mfma_f32_16x16x32_bf16 v[4:7], v[210:213], v[176:179], v[4:7]
	v_mfma_f32_16x16x32_bf16 v[8:11], v[214:217], v[176:179], v[8:11]
	v_mfma_f32_16x16x32_bf16 v[12:15], v[222:225], v[176:179], v[12:15]
	v_mfma_f32_16x16x32_bf16 v[16:19], v[204:207], v[180:183], v[16:19]
	v_mfma_f32_16x16x32_bf16 v[20:23], v[210:213], v[180:183], v[20:23]
	v_mfma_f32_16x16x32_bf16 v[24:27], v[214:217], v[180:183], v[24:27]
	v_mfma_f32_16x16x32_bf16 v[28:31], v[222:225], v[180:183], v[28:31]
	v_mfma_f32_16x16x32_bf16 v[32:35], v[204:207], v[184:187], v[32:35]
	v_mfma_f32_16x16x32_bf16 v[36:39], v[210:213], v[184:187], v[36:39]
	v_mfma_f32_16x16x32_bf16 v[40:43], v[214:217], v[184:187], v[40:43]
	v_mfma_f32_16x16x32_bf16 v[44:47], v[222:225], v[184:187], v[44:47]
	v_mfma_f32_16x16x32_bf16 v[48:51], v[204:207], v[188:191], v[48:51]
	v_mfma_f32_16x16x32_bf16 v[52:55], v[210:213], v[188:191], v[52:55]
	v_mfma_f32_16x16x32_bf16 v[56:59], v[214:217], v[188:191], v[56:59]
	v_mfma_f32_16x16x32_bf16 v[60:63], v[222:225], v[188:191], v[60:63]
	s_setprio 0
	ds_read_b128 v[176:179], v221 offset:1024
	ds_read_b128 v[180:183], v221 offset:3072
	ds_read_b128 v[184:187], v221 offset:5120
	ds_read_b128 v[188:191], v221 offset:7168
	ds_read_b128 v[64:67], v226 offset:33792
	ds_read_b128 v[68:71], v226 offset:35840
	ds_read_b128 v[72:75], v226 offset:37888
	ds_read_b128 v[76:79], v226 offset:39936
	s_setprio 1
	s_waitcnt lgkmcnt(8)
; #define WAIT_V0() asm volatile("s_waitcnt vmcnt(0)" ::: "memory")
; #define G_STAGE_B(Bp, buf, kt) do { const char* bb_ = (const char*)(Bp) + (size_t)(kt) * 128; \
;       _Pragma("unroll") for (int i = 0; i < 4; ++i) \
;         __builtin_amdgcn_global_load_lds((const unsigned*)(bb_ + soff[i]), (LDSP unsigned*)(G_SB(buf) + wid * 1024 + i * 8192), 16, 0, 0); } while (0)
; #define G_RDA(AF, buf, ks, mh) do { _Pragma("unroll") for (int m = 0; m < 4; ++m) AF[m] = *(const LDSP bf16x8*)(G_SA(buf) + aoff + ((mh) * 4 + m) * 2048 + (ks) * 1024); } while (0)
; #define G_RDB(BF, buf, ks) do { _Pragma("unroll") for (int n = 0; n < 4; ++n) BF[n] = *(const LDSP bf16x8*)(G_SB(buf) + boff + n * 2048 + (ks) * 1024); } while (0)
; #define G_MMA(AF, BF, mh) do { __builtin_amdgcn_s_setprio(1); \
;             _Pragma("unroll") for (int m = 0; m < 4; ++m) _Pragma("unroll") for (int n = 0; n < 4; ++n) \
;                 acc[(mh) * 4 + m][n] = __builtin_amdgcn_mfma_f32_16x16x32_bf16(BF[n], AF[m], acc[(mh) * 4 + m][n], 0, 0, 0); \
;             __builtin_amdgcn_s_setprio(0); } while (0)
; #define G_SB0() __builtin_amdgcn_sched_barrier(0)
; template <int EK>
; DI void gemm_stream(const Params& p, int l, const bf16_t* __restrict__ A, const bf16_t* __restrict__ Bt, int M, int N, int K, ldsp_t shm) {
;     ...
;             G_RDA(Aa, cur, 0, 0); G_RDB(Bk0, cur, 0);
;             if (t + 1 < nt) G_STAGE_B(Bb, cur ^ 1, t + 1);
;             else if (has_next) G_STAGE_B(Bb2, cur ^ 1, 0);
;     ...
;             G_RDA(Aa, cur, 1, 0); G_RDB(Bk1, cur, 1);
;             G_MMA(Ab_, Bk0, 1); G_SB0();
;             G_RDA(Ab_, cur, 1, 1);
;             G_MMA(Aa, Bk1, 0); G_SB0();
;             asm volatile("s_waitcnt lgkmcnt(0)" ::: "memory");
;             WAIT_V0(); __syncthreads();
;         }
	v_mfma_f32_16x16x32_bf16 v[140:143], v[204:207], v[144:147], v[140:143]
	v_mfma_f32_16x16x32_bf16 v[136:139], v[210:213], v[144:147], v[136:139]
	v_mfma_f32_16x16x32_bf16 v[132:135], v[214:217], v[144:147], v[132:135]
	v_mfma_f32_16x16x32_bf16 v[128:131], v[222:225], v[144:147], v[128:131]
	v_mfma_f32_16x16x32_bf16 v[124:127], v[204:207], v[148:151], v[124:127]
	v_mfma_f32_16x16x32_bf16 v[120:123], v[210:213], v[148:151], v[120:123]
	v_mfma_f32_16x16x32_bf16 v[116:119], v[214:217], v[148:151], v[116:119]
	v_mfma_f32_16x16x32_bf16 v[112:115], v[222:225], v[148:151], v[112:115]
	v_mfma_f32_16x16x32_bf16 v[108:111], v[204:207], v[152:155], v[108:111]
	v_mfma_f32_16x16x32_bf16 v[104:107], v[210:213], v[152:155], v[104:107]
	v_mfma_f32_16x16x32_bf16 v[100:103], v[214:217], v[152:155], v[100:103]
	v_mfma_f32_16x16x32_bf16 v[96:99], v[222:225], v[152:155], v[96:99]
	v_mfma_f32_16x16x32_bf16 v[92:95], v[204:207], v[156:159], v[92:95]
	v_mfma_f32_16x16x32_bf16 v[88:91], v[210:213], v[156:159], v[88:91]
	v_mfma_f32_16x16x32_bf16 v[84:87], v[214:217], v[156:159], v[84:87]
	v_mfma_f32_16x16x32_bf16 v[80:83], v[222:225], v[156:159], v[80:83]
	s_setprio 0
	ds_read_b128 v[156:159], v221 offset:9216
	ds_read_b128 v[152:155], v221 offset:11264
	ds_read_b128 v[148:151], v221 offset:13312
	ds_read_b128 v[144:147], v221 offset:15360
	s_setprio 1
	s_waitcnt lgkmcnt(4)
	v_mfma_f32_16x16x32_bf16 v[0:3], v[64:67], v[176:179], v[0:3]
	v_mfma_f32_16x16x32_bf16 v[4:7], v[68:71], v[176:179], v[4:7]
	v_mfma_f32_16x16x32_bf16 v[8:11], v[72:75], v[176:179], v[8:11]
	v_mfma_f32_16x16x32_bf16 v[12:15], v[76:79], v[176:179], v[12:15]
	v_mfma_f32_16x16x32_bf16 v[16:19], v[64:67], v[180:183], v[16:19]
	v_mfma_f32_16x16x32_bf16 v[20:23], v[68:71], v[180:183], v[20:23]
	v_mfma_f32_16x16x32_bf16 v[24:27], v[72:75], v[180:183], v[24:27]
	v_mfma_f32_16x16x32_bf16 v[28:31], v[76:79], v[180:183], v[28:31]
	v_mfma_f32_16x16x32_bf16 v[32:35], v[64:67], v[184:187], v[32:35]
	v_mfma_f32_16x16x32_bf16 v[36:39], v[68:71], v[184:187], v[36:39]
	v_mfma_f32_16x16x32_bf16 v[40:43], v[72:75], v[184:187], v[40:43]
	v_mfma_f32_16x16x32_bf16 v[44:47], v[76:79], v[184:187], v[44:47]
	v_mfma_f32_16x16x32_bf16 v[48:51], v[64:67], v[188:191], v[48:51]
	v_mfma_f32_16x16x32_bf16 v[52:55], v[68:71], v[188:191], v[52:55]
	v_mfma_f32_16x16x32_bf16 v[56:59], v[72:75], v[188:191], v[56:59]
	v_mfma_f32_16x16x32_bf16 v[60:63], v[76:79], v[188:191], v[60:63]
	s_setprio 0
	s_waitcnt lgkmcnt(0)
	s_waitcnt vmcnt(0)
	s_add_u32 s6, s6, 0x80
	s_addc_u32 s7, s7, 0
	s_add_i32 s41, s41, 0x10000
	s_cmpk_eq_i32 s6, 0x700
	s_waitcnt vmcnt(0)
	s_barrier
	s_cbranch_scc0 .LBB0_132
	v_add_u32_e32 v160, 0x10000, v218
	v_add_u32_e32 v161, 0x10800, v218
	ds_read_b128 v[188:191], v160
	ds_read_b128 v[180:183], v161
	v_add_u32_e32 v160, 0x11000, v218
	v_add_u32_e32 v161, 0x11800, v218
	ds_read_b128 v[184:187], v160
	ds_read_b128 v[176:179], v161
	v_or_b32_e32 v160, 0x18000, v219
	v_add_u32_e32 v164, 0x18800, v219
	v_add_u32_e32 v168, 0x19000, v219
	v_add_u32_e32 v172, 0x19800, v219
	ds_read_b128 v[160:163], v160
	ds_read_b128 v[164:167], v164
	ds_read_b128 v[168:171], v168
	ds_read_b128 v[172:175], v172
	s_ashr_i32 s43, s42, 31
	v_cndmask_b32_e64 v200, 0, 1, s[38:39]
	v_cmp_ne_u32_e64 s[6:7], 1, v200
	s_andn2_b64 vcc, exec, s[38:39]
	s_lshl_b64 s[46:47], s[42:43], 19
	s_cbranch_vccnz .LBB0_135
	s_add_u32 s38, s93, s46
	s_addc_u32 s39, s98, s47
	v_add_u32_e32 v212, 0x8000, v220
	v_lshl_add_u64 v[200:201], s[38:39], 0, v[192:193]
	v_lshl_add_u64 v[204:205], s[38:39], 0, v[194:195]
	v_lshl_add_u64 v[206:207], s[38:39], 0, v[196:197]
	v_lshl_add_u64 v[210:211], s[38:39], 0, v[198:199]
	v_add_u32_e32 v215, 0xa000, v220
	v_readfirstlane_b32 s38, v212
	v_add_u32_e32 v214, 0xc000, v220
	s_mov_b32 m0, s38
	v_readfirstlane_b32 s38, v215
	v_add_u32_e32 v213, 0xe000, v220
	global_load_lds_dwordx4 v[200:201], off
	s_mov_b32 m0, s38
	v_readfirstlane_b32 s38, v214
	global_load_lds_dwordx4 v[204:205], off
	s_mov_b32 m0, s38
	v_readfirstlane_b32 s38, v213
	global_load_lds_dwordx4 v[206:207], off
	s_mov_b32 m0, s38
	s_nop 0
	global_load_lds_dwordx4 v[210:211], off

; #define WAIT_V0() asm volatile("s_waitcnt vmcnt(0)" ::: "memory")
; #define G_STAGE_A(Ap, buf, kt) do { const char* ab_ = (const char*)(Ap) + (size_t)(kt) * 128; \
;       _Pragma("unroll") for (int i = 0; i < 4; ++i) \
;         __builtin_amdgcn_global_load_lds((const unsigned*)(ab_ + soff[i]), (LDSP unsigned*)(G_SA(buf) + wid * 1024 + i * 8192), 16, 0, 0); } while (0)
; #define G_STAGE_B(Bp, buf, kt) do { const char* bb_ = (const char*)(Bp) + (size_t)(kt) * 128; \
;       _Pragma("unroll") for (int i = 0; i < 4; ++i) \
;         __builtin_amdgcn_global_load_lds((const unsigned*)(bb_ + soff[i]), (LDSP unsigned*)(G_SB(buf) + wid * 1024 + i * 8192), 16, 0, 0); } while (0)
; #define G_RDA(AF, buf, ks, mh) do { _Pragma("unroll") for (int m = 0; m < 4; ++m) AF[m] = *(const LDSP bf16x8*)(G_SA(buf) + aoff + ((mh) * 4 + m) * 2048 + (ks) * 1024); } while (0)
; #define G_RDB(BF, buf, ks) do { _Pragma("unroll") for (int n = 0; n < 4; ++n) BF[n] = *(const LDSP bf16x8*)(G_SB(buf) + boff + n * 2048 + (ks) * 1024); } while (0)
; #define G_MMA(AF, BF, mh) do { __builtin_amdgcn_s_setprio(1); \
;             _Pragma("unroll") for (int m = 0; m < 4; ++m) _Pragma("unroll") for (int n = 0; n < 4; ++n) \
;                 acc[(mh) * 4 + m][n] = __builtin_amdgcn_mfma_f32_16x16x32_bf16(BF[n], AF[m], acc[(mh) * 4 + m][n], 0, 0, 0); \
;             __builtin_amdgcn_s_setprio(0); } while (0)
; template <int EK>
; DI void gemm_stream(const Params& p, int l, const bf16_t* __restrict__ A, const bf16_t* __restrict__ Bt, int M, int N, int K, ldsp_t shm) {
;     ...
;         for (int t = 0; t < nt; ++t) {
;             const int cur = t & 1;
;             G_RDA(Aa, cur, 0, 0); G_RDB(Bk0, cur, 0);
;             if (t + 1 < nt) G_STAGE_B(Bb, cur ^ 1, t + 1);
;             else if (has_next) G_STAGE_B(Bb2, cur ^ 1, 0);
;             G_SB0();
;             if (t > 0) G_MMA(Ab_, Bk1, 1);
;             G_SB0();
;             if (t + 1 < nt) G_STAGE_A(Ab, cur ^ 1, t + 1);
;             else if (has_next) G_STAGE_A(Ab2, cur ^ 1, 0);
;             G_RDA(Ab_, cur, 0, 1);
;             G_MMA(Aa, Bk0, 0); G_SB0();
;             G_RDA(Aa, cur, 1, 0); G_RDB(Bk1, cur, 1);
;             G_MMA(Ab_, Bk0, 1); G_SB0();
;             G_RDA(Ab_, cur, 1, 1);
;             G_MMA(Aa, Bk1, 0); G_SB0();
;             asm volatile("s_waitcnt lgkmcnt(0)" ::: "memory");
;             WAIT_V0(); __syncthreads();
;         }
.LBB0_191:
	s_and_b32 s6, s43, 0x10000
	v_add_u32_e32 v221, s6, v218
	v_or_b32_e32 v226, s6, v219
	s_xor_b32 s6, s6, 0x10000
	v_add_u32_e32 v227, s6, v220
	v_add_u32_e32 v228, 0x8000, v227
	v_lshl_add_u64 v[200:201], v[160:161], 0, s[4:5]
	v_readfirstlane_b32 s6, v228
	v_add_u32_e32 v228, 0xa000, v227
	s_mov_b32 m0, s6
	v_readfirstlane_b32 s6, v228
	v_add_u32_e32 v228, 0xc000, v227
	ds_read_b128 v[176:179], v221
	ds_read_b128 v[180:183], v221 offset:2048
	ds_read_b128 v[184:187], v221 offset:4096
	ds_read_b128 v[188:191], v221 offset:6144
	ds_read_b128 v[204:207], v226 offset:32768
	ds_read_b128 v[210:213], v226 offset:34816
	ds_read_b128 v[214:217], v226 offset:36864
	ds_read_b128 v[222:225], v226 offset:38912
	global_load_lds_dwordx4 v[200:201], off
	v_lshl_add_u64 v[200:201], v[162:163], 0, s[4:5]
	s_mov_b32 m0, s6
	v_readfirstlane_b32 s6, v228
	v_add_u32_e32 v228, 0xe000, v227
	global_load_lds_dwordx4 v[200:201], off
	v_lshl_add_u64 v[200:201], v[164:165], 0, s[4:5]
	s_mov_b32 m0, s6
	v_readfirstlane_b32 s6, v228
	global_load_lds_dwordx4 v[200:201], off
	v_lshl_add_u64 v[200:201], v[166:167], 0, s[4:5]
	s_mov_b32 m0, s6
	s_nop 0
	global_load_lds_dwordx4 v[200:201], off
	s_setprio 1
	v_mfma_f32_16x16x32_bf16 v[140:143], v[64:67], v[156:159], v[140:143]
	v_mfma_f32_16x16x32_bf16 v[136:139], v[68:71], v[156:159], v[136:139]
	v_mfma_f32_16x16x32_bf16 v[132:135], v[72:75], v[156:159], v[132:135]
	v_mfma_f32_16x16x32_bf16 v[128:131], v[76:79], v[156:159], v[128:131]
	v_mfma_f32_16x16x32_bf16 v[124:127], v[64:67], v[152:155], v[124:127]
	v_mfma_f32_16x16x32_bf16 v[120:123], v[68:71], v[152:155], v[120:123]
	v_mfma_f32_16x16x32_bf16 v[116:119], v[72:75], v[152:155], v[116:119]
	v_mfma_f32_16x16x32_bf16 v[112:115], v[76:79], v[152:155], v[112:115]
	v_mfma_f32_16x16x32_bf16 v[108:111], v[64:67], v[148:151], v[108:111]
	v_mfma_f32_16x16x32_bf16 v[104:107], v[68:71], v[148:151], v[104:107]
	v_mfma_f32_16x16x32_bf16 v[100:103], v[72:75], v[148:151], v[100:103]
	v_mfma_f32_16x16x32_bf16 v[96:99], v[76:79], v[148:151], v[96:99]
	v_mfma_f32_16x16x32_bf16 v[92:95], v[64:67], v[144:147], v[92:95]
	v_mfma_f32_16x16x32_bf16 v[88:91], v[68:71], v[144:147], v[88:91]
	v_mfma_f32_16x16x32_bf16 v[84:87], v[72:75], v[144:147], v[84:87]
	v_mfma_f32_16x16x32_bf16 v[80:83], v[76:79], v[144:147], v[80:83]
	s_setprio 0
	v_readfirstlane_b32 s6, v227
	v_add_u32_e32 v66, 0x2000, v227
	v_lshl_add_u64 v[64:65], v[168:169], 0, s[4:5]
	s_mov_b32 m0, s6
	v_readfirstlane_b32 s6, v66
	v_add_u32_e32 v66, 0x4000, v227
	global_load_lds_dwordx4 v[64:65], off
	v_lshl_add_u64 v[64:65], v[170:171], 0, s[4:5]
	s_mov_b32 m0, s6
	v_readfirstlane_b32 s6, v66
	v_add_u32_e32 v66, 0x6000, v227
	global_load_lds_dwordx4 v[64:65], off
	v_lshl_add_u64 v[64:65], v[172:173], 0, s[4:5]
	s_mov_b32 m0, s6
	v_readfirstlane_b32 s6, v66
	global_load_lds_dwordx4 v[64:65], off
	v_lshl_add_u64 v[64:65], v[174:175], 0, s[4:5]
	s_mov_b32 m0, s6
	s_nop 0
	global_load_lds_dwordx4 v[64:65], off
	ds_read_b128 v[144:147], v221 offset:8192
	ds_read_b128 v[148:151], v221 offset:10240
	ds_read_b128 v[152:155], v221 offset:12288
	ds_read_b128 v[156:159], v221 offset:14336
	s_setprio 1
	s_waitcnt lgkmcnt(4)
	v_mfma_f32_16x16x32_bf16 v[0:3], v[204:207], v[176:179], v[0:3]
	v_mfma_f32_16x16x32_bf16 v[4:7], v[210:213], v[176:179], v[4:7]
	v_mfma_f32_16x16x32_bf16 v[8:11], v[214:217], v[176:179], v[8:11]
	v_mfma_f32_16x16x32_bf16 v[12:15], v[222:225], v[176:179], v[12:15]
	v_mfma_f32_16x16x32_bf16 v[16:19], v[204:207], v[180:183], v[16:19]
	v_mfma_f32_16x16x32_bf16 v[20:23], v[210:213], v[180:183], v[20:23]
	v_mfma_f32_16x16x32_bf16 v[24:27], v[214:217], v[180:183], v[24:27]
	v_mfma_f32_16x16x32_bf16 v[28:31], v[222:225], v[180:183], v[28:31]
	v_mfma_f32_16x16x32_bf16 v[32:35], v[204:207], v[184:187], v[32:35]
	v_mfma_f32_16x16x32_bf16 v[36:39], v[210:213], v[184:187], v[36:39]
	v_mfma_f32_16x16x32_bf16 v[40:43], v[214:217], v[184:187], v[40:43]
	v_mfma_f32_16x16x32_bf16 v[44:47], v[222:225], v[184:187], v[44:47]
	v_mfma_f32_16x16x32_bf16 v[48:51], v[204:207], v[188:191], v[48:51]
	v_mfma_f32_16x16x32_bf16 v[52:55], v[210:213], v[188:191], v[52:55]
	v_mfma_f32_16x16x32_bf16 v[56:59], v[214:217], v[188:191], v[56:59]
	v_mfma_f32_16x16x32_bf16 v[60:63], v[222:225], v[188:191], v[60:63]
	s_setprio 0
	ds_read_b128 v[176:179], v221 offset:1024
	ds_read_b128 v[180:183], v221 offset:3072
	ds_read_b128 v[184:187], v221 offset:5120
	ds_read_b128 v[188:191], v221 offset:7168
	ds_read_b128 v[64:67], v226 offset:33792
	ds_read_b128 v[68:71], v226 offset:35840
	ds_read_b128 v[72:75], v226 offset:37888
	ds_read_b128 v[76:79], v226 offset:39936
	s_setprio 1
	s_waitcnt lgkmcnt(8)
; #define WAIT_V0() asm volatile("s_waitcnt vmcnt(0)" ::: "memory")
; #define G_STAGE_B(Bp, buf, kt) do { const char* bb_ = (const char*)(Bp) + (size_t)(kt) * 128; \
;       _Pragma("unroll") for (int i = 0; i < 4; ++i) \
;         __builtin_amdgcn_global_load_lds((const unsigned*)(bb_ + soff[i]), (LDSP unsigned*)(G_SB(buf) + wid * 1024 + i * 8192), 16, 0, 0); } while (0)
; #define G_RDA(AF, buf, ks, mh) do { _Pragma("unroll") for (int m = 0; m < 4; ++m) AF[m] = *(const LDSP bf16x8*)(G_SA(buf) + aoff + ((mh) * 4 + m) * 2048 + (ks) * 1024); } while (0)
; #define G_RDB(BF, buf, ks) do { _Pragma("unroll") for (int n = 0; n < 4; ++n) BF[n] = *(const LDSP bf16x8*)(G_SB(buf) + boff + n * 2048 + (ks) * 1024); } while (0)
; #define G_MMA(AF, BF, mh) do { __builtin_amdgcn_s_setprio(1); \
;             _Pragma("unroll") for (int m = 0; m < 4; ++m) _Pragma("unroll") for (int n = 0; n < 4; ++n) \
;                 acc[(mh) * 4 + m][n] = __builtin_amdgcn_mfma_f32_16x16x32_bf16(BF[n], AF[m], acc[(mh) * 4 + m][n], 0, 0, 0); \
;             __builtin_amdgcn_s_setprio(0); } while (0)
; #define G_SB0() __builtin_amdgcn_sched_barrier(0)
; template <int EK>
; DI void gemm_stream(const Params& p, int l, const bf16_t* __restrict__ A, const bf16_t* __restrict__ Bt, int M, int N, int K, ldsp_t shm) {
;     ...
;             G_RDA(Aa, cur, 0, 0); G_RDB(Bk0, cur, 0);
;             if (t + 1 < nt) G_STAGE_B(Bb, cur ^ 1, t + 1);
;             else if (has_next) G_STAGE_B(Bb2, cur ^ 1, 0);
;     ...
;             G_RDA(Aa, cur, 1, 0); G_RDB(Bk1, cur, 1);
;             G_MMA(Ab_, Bk0, 1); G_SB0();
;             G_RDA(Ab_, cur, 1, 1);
;             G_MMA(Aa, Bk1, 0); G_SB0();
;             asm volatile("s_waitcnt lgkmcnt(0)" ::: "memory");
;             WAIT_V0(); __syncthreads();
;         }
	v_mfma_f32_16x16x32_bf16 v[140:143], v[204:207], v[144:147], v[140:143]
	v_mfma_f32_16x16x32_bf16 v[136:139], v[210:213], v[144:147], v[136:139]
	v_mfma_f32_16x16x32_bf16 v[132:135], v[214:217], v[144:147], v[132:135]
	v_mfma_f32_16x16x32_bf16 v[128:131], v[222:225], v[144:147], v[128:131]
	v_mfma_f32_16x16x32_bf16 v[124:127], v[204:207], v[148:151], v[124:127]
	v_mfma_f32_16x16x32_bf16 v[120:123], v[210:213], v[148:151], v[120:123]
	v_mfma_f32_16x16x32_bf16 v[116:119], v[214:217], v[148:151], v[116:119]
	v_mfma_f32_16x16x32_bf16 v[112:115], v[222:225], v[148:151], v[112:115]
	v_mfma_f32_16x16x32_bf16 v[108:111], v[204:207], v[152:155], v[108:111]
	v_mfma_f32_16x16x32_bf16 v[104:107], v[210:213], v[152:155], v[104:107]
	v_mfma_f32_16x16x32_bf16 v[100:103], v[214:217], v[152:155], v[100:103]
	v_mfma_f32_16x16x32_bf16 v[96:99], v[222:225], v[152:155], v[96:99]
	v_mfma_f32_16x16x32_bf16 v[92:95], v[204:207], v[156:159], v[92:95]
	v_mfma_f32_16x16x32_bf16 v[88:91], v[210:213], v[156:159], v[88:91]
	v_mfma_f32_16x16x32_bf16 v[84:87], v[214:217], v[156:159], v[84:87]
	v_mfma_f32_16x16x32_bf16 v[80:83], v[222:225], v[156:159], v[80:83]
	s_setprio 0
	ds_read_b128 v[156:159], v221 offset:9216
	ds_read_b128 v[152:155], v221 offset:11264
	ds_read_b128 v[148:151], v221 offset:13312
	ds_read_b128 v[144:147], v221 offset:15360
	s_setprio 1
	s_waitcnt lgkmcnt(4)
	v_mfma_f32_16x16x32_bf16 v[0:3], v[64:67], v[176:179], v[0:3]
	v_mfma_f32_16x16x32_bf16 v[4:7], v[68:71], v[176:179], v[4:7]
	v_mfma_f32_16x16x32_bf16 v[8:11], v[72:75], v[176:179], v[8:11]
	v_mfma_f32_16x16x32_bf16 v[12:15], v[76:79], v[176:179], v[12:15]
	v_mfma_f32_16x16x32_bf16 v[16:19], v[64:67], v[180:183], v[16:19]
	v_mfma_f32_16x16x32_bf16 v[20:23], v[68:71], v[180:183], v[20:23]
	v_mfma_f32_16x16x32_bf16 v[24:27], v[72:75], v[180:183], v[24:27]
	v_mfma_f32_16x16x32_bf16 v[28:31], v[76:79], v[180:183], v[28:31]
	v_mfma_f32_16x16x32_bf16 v[32:35], v[64:67], v[184:187], v[32:35]
	v_mfma_f32_16x16x32_bf16 v[36:39], v[68:71], v[184:187], v[36:39]
	v_mfma_f32_16x16x32_bf16 v[40:43], v[72:75], v[184:187], v[40:43]
	v_mfma_f32_16x16x32_bf16 v[44:47], v[76:79], v[184:187], v[44:47]
	v_mfma_f32_16x16x32_bf16 v[48:51], v[64:67], v[188:191], v[48:51]
	v_mfma_f32_16x16x32_bf16 v[52:55], v[68:71], v[188:191], v[52:55]
	v_mfma_f32_16x16x32_bf16 v[56:59], v[72:75], v[188:191], v[56:59]
	v_mfma_f32_16x16x32_bf16 v[60:63], v[76:79], v[188:191], v[60:63]
	s_setprio 0
	s_waitcnt lgkmcnt(0)
	s_waitcnt vmcnt(0)
	s_add_u32 s4, s4, 0x80
	s_addc_u32 s5, s5, 0
	s_add_i32 s43, s43, 0x10000
	s_cmpk_eq_i32 s4, 0x1f00
	s_waitcnt vmcnt(0)
	s_barrier
	s_cbranch_scc0 .LBB0_191
	v_add_u32_e32 v160, 0x10000, v218
	v_add_u32_e32 v161, 0x10800, v218
	ds_read_b128 v[188:191], v160
	ds_read_b128 v[180:183], v161
	v_add_u32_e32 v160, 0x11000, v218
	v_add_u32_e32 v161, 0x11800, v218
	ds_read_b128 v[184:187], v160
	ds_read_b128 v[176:179], v161
	v_or_b32_e32 v160, 0x18000, v219
	v_add_u32_e32 v164, 0x18800, v219
	v_add_u32_e32 v168, 0x19000, v219
	v_add_u32_e32 v172, 0x19800, v219
	ds_read_b128 v[160:163], v160
	ds_read_b128 v[164:167], v164
	ds_read_b128 v[168:171], v168
	ds_read_b128 v[172:175], v172
	s_ashr_i32 s47, s46, 31
	v_cndmask_b32_e64 v200, 0, 1, s[34:35]
	v_cmp_ne_u32_e64 s[4:5], 1, v200
	s_andn2_b64 vcc, exec, s[34:35]
	s_lshl_b64 s[50:51], s[46:47], 21
	s_cbranch_vccnz .LBB0_194
	s_add_u32 s6, s9, s50
	s_addc_u32 s7, s31, s51
	v_add_u32_e32 v212, 0x8000, v220
	v_lshl_add_u64 v[200:201], s[6:7], 0, v[192:193]
	v_lshl_add_u64 v[204:205], s[6:7], 0, v[194:195]
	v_lshl_add_u64 v[206:207], s[6:7], 0, v[196:197]
	v_lshl_add_u64 v[210:211], s[6:7], 0, v[198:199]
	v_add_u32_e32 v215, 0xa000, v220
	v_readfirstlane_b32 s6, v212
	v_add_u32_e32 v214, 0xc000, v220
	s_mov_b32 m0, s6
	v_readfirstlane_b32 s6, v215
	v_add_u32_e32 v213, 0xe000, v220
	global_load_lds_dwordx4 v[200:201], off
	s_mov_b32 m0, s6
	v_readfirstlane_b32 s6, v214
	global_load_lds_dwordx4 v[204:205], off
	s_mov_b32 m0, s6
	v_readfirstlane_b32 s6, v213
	global_load_lds_dwordx4 v[206:207], off
	s_mov_b32 m0, s6
	s_nop 0
	global_load_lds_dwordx4 v[210:211], off

; #define WAIT_V0() asm volatile("s_waitcnt vmcnt(0)" ::: "memory")
; #define G_STAGE_A(Ap, buf, kt) do { const char* ab_ = (const char*)(Ap) + (size_t)(kt) * 128; \
;       _Pragma("unroll") for (int i = 0; i < 4; ++i) \
;         __builtin_amdgcn_global_load_lds((const unsigned*)(ab_ + soff[i]), (LDSP unsigned*)(G_SA(buf) + wid * 1024 + i * 8192), 16, 0, 0); } while (0)
; #define G_STAGE_B(Bp, buf, kt) do { const char* bb_ = (const char*)(Bp) + (size_t)(kt) * 128; \
;       _Pragma("unroll") for (int i = 0; i < 4; ++i) \
;         __builtin_amdgcn_global_load_lds((const unsigned*)(bb_ + soff[i]), (LDSP unsigned*)(G_SB(buf) + wid * 1024 + i * 8192), 16, 0, 0); } while (0)
; #define G_RDA(AF, buf, ks, mh) do { _Pragma("unroll") for (int m = 0; m < 4; ++m) AF[m] = *(const LDSP bf16x8*)(G_SA(buf) + aoff + ((mh) * 4 + m) * 2048 + (ks) * 1024); } while (0)
; #define G_RDB(BF, buf, ks) do { _Pragma("unroll") for (int n = 0; n < 4; ++n) BF[n] = *(const LDSP bf16x8*)(G_SB(buf) + boff + n * 2048 + (ks) * 1024); } while (0)
; #define G_MMA(AF, BF, mh) do { __builtin_amdgcn_s_setprio(1); \
;             _Pragma("unroll") for (int m = 0; m < 4; ++m) _Pragma("unroll") for (int n = 0; n < 4; ++n) \
;                 acc[(mh) * 4 + m][n] = __builtin_amdgcn_mfma_f32_16x16x32_bf16(BF[n], AF[m], acc[(mh) * 4 + m][n], 0, 0, 0); \
;             __builtin_amdgcn_s_setprio(0); } while (0)
; template <int EK>
; DI void gemm_stream(const Params& p, int l, const bf16_t* __restrict__ A, const bf16_t* __restrict__ Bt, int M, int N, int K, ldsp_t shm) {
;     ...
;         for (int t = 0; t < nt; ++t) {
;             const int cur = t & 1;
;             G_RDA(Aa, cur, 0, 0); G_RDB(Bk0, cur, 0);
;             if (t + 1 < nt) G_STAGE_B(Bb, cur ^ 1, t + 1);
;             else if (has_next) G_STAGE_B(Bb2, cur ^ 1, 0);
;             G_SB0();
;             if (t > 0) G_MMA(Ab_, Bk1, 1);
;             G_SB0();
;             if (t + 1 < nt) G_STAGE_A(Ab, cur ^ 1, t + 1);
;             else if (has_next) G_STAGE_A(Ab2, cur ^ 1, 0);
;             G_RDA(Ab_, cur, 0, 1);
;             G_MMA(Aa, Bk0, 0); G_SB0();
;             G_RDA(Aa, cur, 1, 0); G_RDB(Bk1, cur, 1);
;             G_MMA(Ab_, Bk0, 1); G_SB0();
;             G_RDA(Ab_, cur, 1, 1);
;             G_MMA(Aa, Bk1, 0); G_SB0();
;             asm volatile("s_waitcnt lgkmcnt(0)" ::: "memory");
;             WAIT_V0(); __syncthreads();
;         }
.LBB0_264:
	s_and_b32 s9, s8, 0x10000
	v_add_u32_e32 v221, s9, v218
	v_or_b32_e32 v226, s9, v219
	s_xor_b32 s9, s9, 0x10000
	v_add_u32_e32 v227, s9, v220
	v_add_u32_e32 v228, 0x8000, v227
	v_lshl_add_u64 v[200:201], v[160:161], 0, s[4:5]
	v_readfirstlane_b32 s9, v228
	v_add_u32_e32 v228, 0xa000, v227
	s_mov_b32 m0, s9
	v_readfirstlane_b32 s9, v228
	v_add_u32_e32 v228, 0xc000, v227
	ds_read_b128 v[176:179], v221
	ds_read_b128 v[180:183], v221 offset:2048
	ds_read_b128 v[184:187], v221 offset:4096
	ds_read_b128 v[188:191], v221 offset:6144
	ds_read_b128 v[204:207], v226 offset:32768
	ds_read_b128 v[210:213], v226 offset:34816
	ds_read_b128 v[214:217], v226 offset:36864
	ds_read_b128 v[222:225], v226 offset:38912
	global_load_lds_dwordx4 v[200:201], off
	v_lshl_add_u64 v[200:201], v[162:163], 0, s[4:5]
	s_mov_b32 m0, s9
	v_readfirstlane_b32 s9, v228
	v_add_u32_e32 v228, 0xe000, v227
	global_load_lds_dwordx4 v[200:201], off
	v_lshl_add_u64 v[200:201], v[164:165], 0, s[4:5]
	s_mov_b32 m0, s9
	v_readfirstlane_b32 s9, v228
	global_load_lds_dwordx4 v[200:201], off
	v_lshl_add_u64 v[200:201], v[166:167], 0, s[4:5]
	s_mov_b32 m0, s9
	s_nop 0
	global_load_lds_dwordx4 v[200:201], off
	s_setprio 1
	v_mfma_f32_16x16x32_bf16 v[128:131], v[64:67], v[156:159], v[128:131]
	v_mfma_f32_16x16x32_bf16 v[124:127], v[68:71], v[156:159], v[124:127]
	v_mfma_f32_16x16x32_bf16 v[120:123], v[76:79], v[156:159], v[120:123]
	v_mfma_f32_16x16x32_bf16 v[116:119], v[72:75], v[156:159], v[116:119]
	v_mfma_f32_16x16x32_bf16 v[112:115], v[64:67], v[152:155], v[112:115]
	v_mfma_f32_16x16x32_bf16 v[108:111], v[68:71], v[152:155], v[108:111]
	v_mfma_f32_16x16x32_bf16 v[104:107], v[76:79], v[152:155], v[104:107]
	v_mfma_f32_16x16x32_bf16 v[100:103], v[72:75], v[152:155], v[100:103]
	v_mfma_f32_16x16x32_bf16 v[96:99], v[64:67], v[148:151], v[96:99]
	v_mfma_f32_16x16x32_bf16 v[92:95], v[68:71], v[148:151], v[92:95]
	v_mfma_f32_16x16x32_bf16 v[88:91], v[76:79], v[148:151], v[88:91]
	v_mfma_f32_16x16x32_bf16 v[84:87], v[72:75], v[148:151], v[84:87]
	v_mfma_f32_16x16x32_bf16 v[132:135], v[64:67], v[144:147], v[132:135]
	v_mfma_f32_16x16x32_bf16 v[136:139], v[68:71], v[144:147], v[136:139]
	v_mfma_f32_16x16x32_bf16 v[140:143], v[76:79], v[144:147], v[140:143]
	v_mfma_f32_16x16x32_bf16 v[80:83], v[72:75], v[144:147], v[80:83]
	s_setprio 0
	v_readfirstlane_b32 s9, v227
	v_add_u32_e32 v66, 0x2000, v227
	v_lshl_add_u64 v[64:65], v[168:169], 0, s[4:5]
	s_mov_b32 m0, s9
	v_readfirstlane_b32 s9, v66
	v_add_u32_e32 v66, 0x4000, v227
	global_load_lds_dwordx4 v[64:65], off
	v_lshl_add_u64 v[64:65], v[170:171], 0, s[4:5]
	s_mov_b32 m0, s9
	v_readfirstlane_b32 s9, v66
	v_add_u32_e32 v66, 0x6000, v227
	global_load_lds_dwordx4 v[64:65], off
	v_lshl_add_u64 v[64:65], v[172:173], 0, s[4:5]
	s_mov_b32 m0, s9
	v_readfirstlane_b32 s9, v66
	global_load_lds_dwordx4 v[64:65], off
	v_lshl_add_u64 v[64:65], v[174:175], 0, s[4:5]
	s_mov_b32 m0, s9
	s_nop 0
	global_load_lds_dwordx4 v[64:65], off
	ds_read_b128 v[144:147], v221 offset:8192
	ds_read_b128 v[148:151], v221 offset:10240
	ds_read_b128 v[152:155], v221 offset:12288
	ds_read_b128 v[156:159], v221 offset:14336
	s_setprio 1
	s_waitcnt lgkmcnt(4)
	v_mfma_f32_16x16x32_bf16 v[0:3], v[204:207], v[176:179], v[0:3]
	v_mfma_f32_16x16x32_bf16 v[4:7], v[210:213], v[176:179], v[4:7]
	v_mfma_f32_16x16x32_bf16 v[8:11], v[214:217], v[176:179], v[8:11]
	v_mfma_f32_16x16x32_bf16 v[12:15], v[222:225], v[176:179], v[12:15]
	v_mfma_f32_16x16x32_bf16 v[16:19], v[204:207], v[180:183], v[16:19]
	v_mfma_f32_16x16x32_bf16 v[20:23], v[210:213], v[180:183], v[20:23]
	v_mfma_f32_16x16x32_bf16 v[24:27], v[214:217], v[180:183], v[24:27]
	v_mfma_f32_16x16x32_bf16 v[28:31], v[222:225], v[180:183], v[28:31]
	v_mfma_f32_16x16x32_bf16 v[32:35], v[204:207], v[184:187], v[32:35]
	v_mfma_f32_16x16x32_bf16 v[36:39], v[210:213], v[184:187], v[36:39]
	v_mfma_f32_16x16x32_bf16 v[40:43], v[214:217], v[184:187], v[40:43]
	v_mfma_f32_16x16x32_bf16 v[44:47], v[222:225], v[184:187], v[44:47]
	v_mfma_f32_16x16x32_bf16 v[48:51], v[204:207], v[188:191], v[48:51]
	v_mfma_f32_16x16x32_bf16 v[52:55], v[210:213], v[188:191], v[52:55]
	v_mfma_f32_16x16x32_bf16 v[56:59], v[214:217], v[188:191], v[56:59]
	v_mfma_f32_16x16x32_bf16 v[60:63], v[222:225], v[188:191], v[60:63]
	s_setprio 0
	ds_read_b128 v[176:179], v221 offset:1024
	ds_read_b128 v[180:183], v221 offset:3072
	ds_read_b128 v[184:187], v221 offset:5120
	ds_read_b128 v[188:191], v221 offset:7168
	ds_read_b128 v[64:67], v226 offset:33792
	ds_read_b128 v[68:71], v226 offset:35840
	ds_read_b128 v[76:79], v226 offset:37888
	ds_read_b128 v[72:75], v226 offset:39936
	s_setprio 1
	s_waitcnt lgkmcnt(8)
; #define WAIT_V0() asm volatile("s_waitcnt vmcnt(0)" ::: "memory")
; #define G_STAGE_B(Bp, buf, kt) do { const char* bb_ = (const char*)(Bp) + (size_t)(kt) * 128; \
;       _Pragma("unroll") for (int i = 0; i < 4; ++i) \
;         __builtin_amdgcn_global_load_lds((const unsigned*)(bb_ + soff[i]), (LDSP unsigned*)(G_SB(buf) + wid * 1024 + i * 8192), 16, 0, 0); } while (0)
; #define G_RDA(AF, buf, ks, mh) do { _Pragma("unroll") for (int m = 0; m < 4; ++m) AF[m] = *(const LDSP bf16x8*)(G_SA(buf) + aoff + ((mh) * 4 + m) * 2048 + (ks) * 1024); } while (0)
; #define G_RDB(BF, buf, ks) do { _Pragma("unroll") for (int n = 0; n < 4; ++n) BF[n] = *(const LDSP bf16x8*)(G_SB(buf) + boff + n * 2048 + (ks) * 1024); } while (0)
; #define G_MMA(AF, BF, mh) do { __builtin_amdgcn_s_setprio(1); \
;             _Pragma("unroll") for (int m = 0; m < 4; ++m) _Pragma("unroll") for (int n = 0; n < 4; ++n) \
;                 acc[(mh) * 4 + m][n] = __builtin_amdgcn_mfma_f32_16x16x32_bf16(BF[n], AF[m], acc[(mh) * 4 + m][n], 0, 0, 0); \
;             __builtin_amdgcn_s_setprio(0); } while (0)
; #define G_SB0() __builtin_amdgcn_sched_barrier(0)
; template <int EK>
; DI void gemm_stream(const Params& p, int l, const bf16_t* __restrict__ A, const bf16_t* __restrict__ Bt, int M, int N, int K, ldsp_t shm) {
;     ...
;             G_RDA(Aa, cur, 0, 0); G_RDB(Bk0, cur, 0);
;             if (t + 1 < nt) G_STAGE_B(Bb, cur ^ 1, t + 1);
;             else if (has_next) G_STAGE_B(Bb2, cur ^ 1, 0);
;     ...
;             G_RDA(Aa, cur, 1, 0); G_RDB(Bk1, cur, 1);
;             G_MMA(Ab_, Bk0, 1); G_SB0();
;             G_RDA(Ab_, cur, 1, 1);
;             G_MMA(Aa, Bk1, 0); G_SB0();
;             asm volatile("s_waitcnt lgkmcnt(0)" ::: "memory");
;             WAIT_V0(); __syncthreads();
;         }
	v_mfma_f32_16x16x32_bf16 v[128:131], v[204:207], v[144:147], v[128:131]
	v_mfma_f32_16x16x32_bf16 v[124:127], v[210:213], v[144:147], v[124:127]
	v_mfma_f32_16x16x32_bf16 v[120:123], v[214:217], v[144:147], v[120:123]
	v_mfma_f32_16x16x32_bf16 v[116:119], v[222:225], v[144:147], v[116:119]
	v_mfma_f32_16x16x32_bf16 v[112:115], v[204:207], v[148:151], v[112:115]
	v_mfma_f32_16x16x32_bf16 v[108:111], v[210:213], v[148:151], v[108:111]
	v_mfma_f32_16x16x32_bf16 v[104:107], v[214:217], v[148:151], v[104:107]
	v_mfma_f32_16x16x32_bf16 v[100:103], v[222:225], v[148:151], v[100:103]
	v_mfma_f32_16x16x32_bf16 v[96:99], v[204:207], v[152:155], v[96:99]
	v_mfma_f32_16x16x32_bf16 v[92:95], v[210:213], v[152:155], v[92:95]
	v_mfma_f32_16x16x32_bf16 v[88:91], v[214:217], v[152:155], v[88:91]
	v_mfma_f32_16x16x32_bf16 v[84:87], v[222:225], v[152:155], v[84:87]
	v_mfma_f32_16x16x32_bf16 v[132:135], v[204:207], v[156:159], v[132:135]
	v_mfma_f32_16x16x32_bf16 v[136:139], v[210:213], v[156:159], v[136:139]
	v_mfma_f32_16x16x32_bf16 v[140:143], v[214:217], v[156:159], v[140:143]
	v_mfma_f32_16x16x32_bf16 v[80:83], v[222:225], v[156:159], v[80:83]
	s_setprio 0
	ds_read_b128 v[156:159], v221 offset:9216
	ds_read_b128 v[152:155], v221 offset:11264
	ds_read_b128 v[148:151], v221 offset:13312
	ds_read_b128 v[144:147], v221 offset:15360
	s_setprio 1
	s_waitcnt lgkmcnt(4)
	v_mfma_f32_16x16x32_bf16 v[0:3], v[64:67], v[176:179], v[0:3]
	v_mfma_f32_16x16x32_bf16 v[4:7], v[68:71], v[176:179], v[4:7]
	v_mfma_f32_16x16x32_bf16 v[8:11], v[76:79], v[176:179], v[8:11]
	v_mfma_f32_16x16x32_bf16 v[12:15], v[72:75], v[176:179], v[12:15]
	v_mfma_f32_16x16x32_bf16 v[16:19], v[64:67], v[180:183], v[16:19]
	v_mfma_f32_16x16x32_bf16 v[20:23], v[68:71], v[180:183], v[20:23]
	v_mfma_f32_16x16x32_bf16 v[24:27], v[76:79], v[180:183], v[24:27]
	v_mfma_f32_16x16x32_bf16 v[28:31], v[72:75], v[180:183], v[28:31]
	v_mfma_f32_16x16x32_bf16 v[32:35], v[64:67], v[184:187], v[32:35]
	v_mfma_f32_16x16x32_bf16 v[36:39], v[68:71], v[184:187], v[36:39]
	v_mfma_f32_16x16x32_bf16 v[40:43], v[76:79], v[184:187], v[40:43]
	v_mfma_f32_16x16x32_bf16 v[44:47], v[72:75], v[184:187], v[44:47]
	v_mfma_f32_16x16x32_bf16 v[48:51], v[64:67], v[188:191], v[48:51]
	v_mfma_f32_16x16x32_bf16 v[52:55], v[68:71], v[188:191], v[52:55]
	v_mfma_f32_16x16x32_bf16 v[56:59], v[76:79], v[188:191], v[56:59]
	v_mfma_f32_16x16x32_bf16 v[60:63], v[72:75], v[188:191], v[60:63]
	s_setprio 0
	s_waitcnt lgkmcnt(0)
	s_waitcnt vmcnt(0)
	s_add_u32 s4, s4, 0x80
	s_addc_u32 s5, s5, 0
	s_add_i32 s8, s8, 0x10000
	s_cmpk_eq_i32 s4, 0x700
	s_waitcnt vmcnt(0)
	s_barrier
	s_cbranch_scc0 .LBB0_264
	v_add_u32_e32 v160, 0x10000, v218
	v_add_u32_e32 v161, 0x10800, v218
	ds_read_b128 v[188:191], v160
	ds_read_b128 v[180:183], v161
	v_add_u32_e32 v160, 0x11000, v218
	v_add_u32_e32 v161, 0x11800, v218
	ds_read_b128 v[184:187], v160
	ds_read_b128 v[176:179], v161
	v_or_b32_e32 v160, 0x18000, v219
	v_add_u32_e32 v164, 0x18800, v219
	v_add_u32_e32 v168, 0x19000, v219
	v_add_u32_e32 v172, 0x19800, v219
	ds_read_b128 v[160:163], v160
	ds_read_b128 v[164:167], v164
	ds_read_b128 v[168:171], v168
	ds_read_b128 v[172:175], v172
	s_ashr_i32 s43, s42, 31
	v_cndmask_b32_e64 v200, 0, 1, s[6:7]
	v_cmp_ne_u32_e64 s[4:5], 1, v200
	s_andn2_b64 vcc, exec, s[6:7]
	s_lshl_b64 s[46:47], s[42:43], 19
	s_cbranch_vccnz .LBB0_267
	s_add_u32 s6, s14, s46
	s_addc_u32 s7, s15, s47
	v_add_u32_e32 v212, 0x8000, v220
	v_lshl_add_u64 v[200:201], s[6:7], 0, v[192:193]
	v_lshl_add_u64 v[204:205], s[6:7], 0, v[194:195]
	v_lshl_add_u64 v[206:207], s[6:7], 0, v[196:197]
	v_lshl_add_u64 v[210:211], s[6:7], 0, v[198:199]
	v_add_u32_e32 v215, 0xa000, v220
	v_readfirstlane_b32 s6, v212
	v_add_u32_e32 v214, 0xc000, v220
	s_mov_b32 m0, s6
	v_readfirstlane_b32 s6, v215
	v_add_u32_e32 v213, 0xe000, v220
	global_load_lds_dwordx4 v[200:201], off
	s_mov_b32 m0, s6
	v_readfirstlane_b32 s6, v214
	global_load_lds_dwordx4 v[204:205], off
	s_mov_b32 m0, s6
	v_readfirstlane_b32 s6, v213
	global_load_lds_dwordx4 v[206:207], off
	s_mov_b32 m0, s6
	s_nop 0
	global_load_lds_dwordx4 v[210:211], off
